# attn-softmax-PV-block-split: counted vmcnt keeps next-K prefetch in flight across PV MFMAs (prompt attention P3/P4)
# speedup vs baseline: 1.0022x; 1.0022x over previous
; DI float fexp2(float x) { return __builtin_amdgcn_exp2f(x); }
; DI bf16x8 pack_step(const f32x16& x, int s) { u32x4 p; p.x = pk2(x[8 * s], x[8 * s + 1]); p.y = pk2(x[8 * s + 2], x[8 * s + 3]); p.z = pk2(x[8 * s + 4], x[8 * s + 5]); p.w = pk2(x[8 * s + 6], x[8 * s + 7]); return __builtin_bit_cast(bf16x8, p); }
; #define MFMA32(a, b, c) __builtin_amdgcn_mfma_f32_32x32x16_bf16((a), (b), (c), 0, 0, 0)
; template <class T> DI void attn_item(const T& t) {
;     ...
;         float ps = 0.f;
; #pragma unroll
;         for (int i = 0; i < 16; ++i) { const float p = fexp2(s[i] - m); s[i] = p; ps += p; }
;         ps += __shfl_xor(ps, 32);
;         l += ps;
; #pragma unroll
;         for (int s2 = 0; s2 < 2; ++s2) { const bf16x8 pb = pack_step(s, s2);
;             if (T::VSPLIT) {
; #pragma unroll
;                 for (int dd = 0; dd < D / 32; ++dd) vf[s2][dd] = t.vfrag_t(tl, s2, dd);
;             }
; #pragma unroll
;             for (int dd = 0; dd < D / 32; ++dd) o[dd] = MFMA32(vf[s2][dd], pb, o[dd]); }
.LBB0_971:
	s_cmp_eq_u32 s79, s40
	s_cbranch_scc1 .Latt_sw3_last
	v_sub_f32_e32 v36, v36, v126
	v_exp_f32_e32 v36, v36
	v_sub_f32_e32 v37, v37, v126
	v_exp_f32_e32 v37, v37
	v_sub_f32_e32 v38, v38, v126
	v_exp_f32_e32 v38, v38
	v_sub_f32_e32 v39, v39, v126
	v_exp_f32_e32 v39, v39
	v_sub_f32_e32 v40, v40, v126
	v_add_f32_e32 v127, 0, v36
	v_exp_f32_e32 v40, v40
	v_sub_f32_e32 v41, v41, v126
	v_add_f32_e32 v127, v37, v127
	v_exp_f32_e32 v41, v41
	v_sub_f32_e32 v42, v42, v126
	v_sub_f32_e32 v43, v43, v126
	v_add_f32_e32 v127, v38, v127
	v_exp_f32_e32 v42, v42
	v_exp_f32_e32 v43, v43
	v_add_f32_e32 v127, v39, v127
	v_sub_f32_e32 v44, v44, v126
	v_add_f32_e32 v127, v40, v127
	v_exp_f32_e32 v44, v44
	v_sub_f32_e32 v45, v45, v126
	v_add_f32_e32 v127, v41, v127
	v_exp_f32_e32 v45, v45
	v_sub_f32_e32 v46, v46, v126
	v_add_f32_e32 v127, v42, v127
	v_exp_f32_e32 v46, v46
	v_sub_f32_e32 v47, v47, v126
	v_cvt_pk_bf16_f32 v36, v36, v37
	v_cvt_pk_bf16_f32 v37, v38, v39
	v_cvt_pk_bf16_f32 v38, v40, v41
	v_cvt_pk_bf16_f32 v39, v42, v43
	v_add_f32_e32 v127, v43, v127
	v_exp_f32_e32 v47, v47
	v_sub_f32_e32 v48, v48, v126
	s_waitcnt vmcnt(7)
	v_mfma_f32_32x32x16_bf16 v[20:35], v[96:99], v[36:39], v[20:35]
	v_add_f32_e32 v127, v44, v127
	v_exp_f32_e32 v40, v48
	v_sub_f32_e32 v41, v49, v126
	v_add_f32_e32 v127, v45, v127
	v_exp_f32_e32 v41, v41
	v_sub_f32_e32 v42, v50, v126
	v_add_f32_e32 v127, v46, v127
	s_waitcnt vmcnt(6)
	v_mfma_f32_32x32x16_bf16 v[4:19], v[92:95], v[36:39], v[4:19]
	v_sub_f32_e32 v36, v51, v126
	v_exp_f32_e32 v42, v42
	v_exp_f32_e32 v48, v36
	v_add_f32_e32 v127, v47, v127
	v_add_f32_e32 v43, v40, v127
	v_add_f32_e32 v43, v41, v43
	v_add_f32_e32 v43, v42, v43
	v_cvt_pk_bf16_f32 v36, v44, v45
	v_cvt_pk_bf16_f32 v37, v46, v47
	v_cvt_pk_bf16_f32 v38, v40, v41
	v_cvt_pk_bf16_f32 v39, v42, v48
	v_add_f32_e32 v40, v48, v43
	ds_bpermute_b32 v41, v103, v40
	s_waitcnt vmcnt(5)
	v_mfma_f32_32x32x16_bf16 v[20:35], v[88:91], v[36:39], v[20:35]
	s_add_u32 s40, s40, 0x1000
	s_addc_u32 s41, s41, 0
	s_add_i32 s72, s72, 32
	s_waitcnt lgkmcnt(0)
	v_add_f32_e32 v40, v40, v41
	s_cmp_eq_u32 s86, s40
	v_add_f32_e32 v125, v125, v40
	s_waitcnt vmcnt(4)
	v_mfma_f32_32x32x16_bf16 v[4:19], v[84:87], v[36:39], v[4:19]
	s_branch .LBB0_972

; DI float fexp2(float x) { return __builtin_amdgcn_exp2f(x); }
; DI bf16x8 pack_step(const f32x16& x, int s) { u32x4 p; p.x = pk2(x[8 * s], x[8 * s + 1]); p.y = pk2(x[8 * s + 2], x[8 * s + 3]); p.z = pk2(x[8 * s + 4], x[8 * s + 5]); p.w = pk2(x[8 * s + 6], x[8 * s + 7]); return __builtin_bit_cast(bf16x8, p); }
; #define MFMA32(a, b, c) __builtin_amdgcn_mfma_f32_32x32x16_bf16((a), (b), (c), 0, 0, 0)
; template <class T> DI void attn_item(const T& t) {
;     ...
;         float ps = 0.f;
; #pragma unroll
;         for (int i = 0; i < 16; ++i) { const float p = fexp2(s[i] - m); s[i] = p; ps += p; }
;         ps += __shfl_xor(ps, 32);
;         l += ps;
; #pragma unroll
;         for (int s2 = 0; s2 < 2; ++s2) { const bf16x8 pb = pack_step(s, s2);
;             if (T::VSPLIT) {
; #pragma unroll
;                 for (int dd = 0; dd < D / 32; ++dd) vf[s2][dd] = t.vfrag_t(tl, s2, dd);
;             }
; #pragma unroll
;             for (int dd = 0; dd < D / 32; ++dd) o[dd] = MFMA32(vf[s2][dd], pb, o[dd]); }
.LBB0_982:
	s_cmpk_eq_u32 s40, 0xe000
	s_cbranch_scc1 .Latt_mm3_last
	v_sub_f32_e32 v2, v82, v224
	v_sub_f32_e32 v16, v83, v224
	v_sub_f32_e32 v82, v85, v224
	v_exp_f32_e32 v2, v2
	v_exp_f32_e32 v16, v16
	v_exp_f32_e32 v225, v82
	v_sub_f32_e32 v82, v86, v224
	v_sub_f32_e32 v17, v84, v224
	v_exp_f32_e32 v86, v82
	v_sub_f32_e32 v82, v87, v224
	v_exp_f32_e32 v17, v17
	v_exp_f32_e32 v87, v82
	v_sub_f32_e32 v82, v88, v224
	v_exp_f32_e32 v88, v82
	v_sub_f32_e32 v82, v89, v224
	v_exp_f32_e32 v89, v82
	v_cvt_pk_bf16_f32 v82, v2, v16
	v_add_f32_e32 v2, 0, v2
	v_add_f32_e32 v2, v16, v2
	v_add_f32_e32 v2, v17, v2
	v_sub_f32_e32 v90, v90, v224
	v_add_f32_e32 v2, v225, v2
	v_exp_f32_e32 v90, v90
	v_sub_f32_e32 v91, v91, v224
	v_add_f32_e32 v2, v86, v2
	v_exp_f32_e32 v91, v91
	v_sub_f32_e32 v92, v92, v224
	v_add_f32_e32 v2, v87, v2
	v_cvt_pk_bf16_f32 v83, v17, v225
	v_cvt_pk_bf16_f32 v84, v86, v87
	v_cvt_pk_bf16_f32 v85, v88, v89
	v_exp_f32_e32 v92, v92
	v_sub_f32_e32 v93, v93, v224
	v_add_f32_e32 v2, v88, v2
	s_waitcnt vmcnt(13)
	v_mfma_f32_32x32x16_bf16 v[66:81], v[178:181], v[82:85], v[66:81]
	v_exp_f32_e32 v93, v93
	v_sub_f32_e32 v94, v94, v224
	v_add_f32_e32 v2, v89, v2
	v_exp_f32_e32 v94, v94
	v_sub_f32_e32 v95, v95, v224
	v_add_f32_e32 v2, v90, v2
	v_exp_f32_e32 v95, v95
	v_mfma_f32_32x32x16_bf16 v[50:65], v[174:177], v[82:85], v[50:65]
	v_sub_f32_e32 v96, v96, v224
	v_add_f32_e32 v2, v91, v2
	v_exp_f32_e32 v96, v96
	v_add_f32_e32 v2, v92, v2
	v_add_f32_e32 v2, v93, v2
	v_add_f32_e32 v2, v94, v2
	v_add_f32_e32 v2, v95, v2
	v_mfma_f32_32x32x16_bf16 v[34:49], v[170:173], v[82:85], v[34:49]
	v_add_f32_e32 v2, v96, v2
	s_add_u32 s40, s40, 0x2000
	s_addc_u32 s41, s41, 0
	s_cmp_eq_u32 s40, 0x10000
	s_waitcnt vmcnt(12)
	v_mfma_f32_32x32x16_bf16 v[18:33], v[166:169], v[82:85], v[18:33]
	v_sub_f32_e32 v82, v97, v224
	v_exp_f32_e32 v97, v82
	v_cvt_pk_bf16_f32 v82, v90, v91
	v_cvt_pk_bf16_f32 v83, v92, v93
	v_cvt_pk_bf16_f32 v84, v94, v95
	v_cvt_pk_bf16_f32 v85, v96, v97
	v_add_f32_e32 v2, v97, v2
	s_waitcnt vmcnt(11)
	v_mfma_f32_32x32x16_bf16 v[66:81], v[162:165], v[82:85], v[66:81]
	s_waitcnt vmcnt(10)
	v_mfma_f32_32x32x16_bf16 v[50:65], v[12:15], v[82:85], v[50:65]
	s_waitcnt vmcnt(9)
	v_mfma_f32_32x32x16_bf16 v[34:49], v[8:11], v[82:85], v[34:49]
	ds_bpermute_b32 v8, v222, v2
	s_waitcnt lgkmcnt(0)
	v_add_f32_e32 v2, v2, v8
	v_add_f32_e32 v223, v223, v2
	s_waitcnt vmcnt(8)
	v_mfma_f32_32x32x16_bf16 v[18:33], v[4:7], v[82:85], v[18:33]
	s_branch .LBB0_983

; DI float fexp2(float x) { return __builtin_amdgcn_exp2f(x); }
; DI bf16x8 pack_step(const f32x16& x, int s) { u32x4 p; p.x = pk2(x[8 * s], x[8 * s + 1]); p.y = pk2(x[8 * s + 2], x[8 * s + 3]); p.z = pk2(x[8 * s + 4], x[8 * s + 5]); p.w = pk2(x[8 * s + 6], x[8 * s + 7]); return __builtin_bit_cast(bf16x8, p); }
; #define MFMA32(a, b, c) __builtin_amdgcn_mfma_f32_32x32x16_bf16((a), (b), (c), 0, 0, 0)
; template <class T> DI void attn_item(const T& t) {
;     ...
;         float ps = 0.f;
; #pragma unroll
;         for (int i = 0; i < 16; ++i) { const float p = fexp2(s[i] - m); s[i] = p; ps += p; }
;         ps += __shfl_xor(ps, 32);
;         l += ps;
; #pragma unroll
;         for (int s2 = 0; s2 < 2; ++s2) { const bf16x8 pb = pack_step(s, s2);
;             if (T::VSPLIT) {
; #pragma unroll
;                 for (int dd = 0; dd < D / 32; ++dd) vf[s2][dd] = t.vfrag_t(tl, s2, dd);
;             }
; #pragma unroll
;             for (int dd = 0; dd < D / 32; ++dd) o[dd] = MFMA32(vf[s2][dd], pb, o[dd]); }
.LBB0_1081:
	s_cmp_eq_u32 s77, s40
	s_cbranch_scc1 .Latt_sw4_last
	v_sub_f32_e32 v36, v36, v126
	v_exp_f32_e32 v36, v36
	v_sub_f32_e32 v37, v37, v126
	v_exp_f32_e32 v37, v37
	v_sub_f32_e32 v38, v38, v126
	v_exp_f32_e32 v38, v38
	v_sub_f32_e32 v39, v39, v126
	v_exp_f32_e32 v39, v39
	v_sub_f32_e32 v40, v40, v126
	v_add_f32_e32 v127, 0, v36
	v_exp_f32_e32 v40, v40
	v_sub_f32_e32 v41, v41, v126
	v_add_f32_e32 v127, v37, v127
	v_exp_f32_e32 v41, v41
	v_sub_f32_e32 v42, v42, v126
	v_sub_f32_e32 v43, v43, v126
	v_add_f32_e32 v127, v38, v127
	v_exp_f32_e32 v42, v42
	v_exp_f32_e32 v43, v43
	v_add_f32_e32 v127, v39, v127
	v_sub_f32_e32 v44, v44, v126
	v_add_f32_e32 v127, v40, v127
	v_exp_f32_e32 v44, v44
	v_sub_f32_e32 v45, v45, v126
	v_add_f32_e32 v127, v41, v127
	v_exp_f32_e32 v45, v45
	v_sub_f32_e32 v46, v46, v126
	v_add_f32_e32 v127, v42, v127
	v_exp_f32_e32 v46, v46
	v_sub_f32_e32 v47, v47, v126
	v_cvt_pk_bf16_f32 v36, v36, v37
	v_cvt_pk_bf16_f32 v37, v38, v39
	v_cvt_pk_bf16_f32 v38, v40, v41
	v_cvt_pk_bf16_f32 v39, v42, v43
	v_add_f32_e32 v127, v43, v127
	v_exp_f32_e32 v47, v47
	v_sub_f32_e32 v48, v48, v126
	s_waitcnt vmcnt(7)
	v_mfma_f32_32x32x16_bf16 v[20:35], v[96:99], v[36:39], v[20:35]
	v_add_f32_e32 v127, v44, v127
	v_exp_f32_e32 v40, v48
	v_sub_f32_e32 v41, v49, v126
	v_add_f32_e32 v127, v45, v127
	v_exp_f32_e32 v41, v41
	v_sub_f32_e32 v42, v50, v126
	v_add_f32_e32 v127, v46, v127
	s_waitcnt vmcnt(6)
	v_mfma_f32_32x32x16_bf16 v[4:19], v[92:95], v[36:39], v[4:19]
	v_sub_f32_e32 v36, v51, v126
	v_exp_f32_e32 v42, v42
	v_exp_f32_e32 v48, v36
	v_add_f32_e32 v127, v47, v127
	v_add_f32_e32 v43, v40, v127
	v_add_f32_e32 v43, v41, v43
	v_add_f32_e32 v43, v42, v43
	v_cvt_pk_bf16_f32 v36, v44, v45
	v_cvt_pk_bf16_f32 v37, v46, v47
	v_cvt_pk_bf16_f32 v38, v40, v41
	v_cvt_pk_bf16_f32 v39, v42, v48
	v_add_f32_e32 v40, v48, v43
	ds_bpermute_b32 v41, v103, v40
	s_waitcnt vmcnt(5)
	v_mfma_f32_32x32x16_bf16 v[20:35], v[88:91], v[36:39], v[20:35]
	s_add_u32 s40, s40, 0x1000
	s_addc_u32 s41, s41, 0
	s_add_i32 s74, s74, 32
	s_waitcnt lgkmcnt(0)
	v_add_f32_e32 v40, v40, v41
	s_cmp_eq_u32 s84, s40
	v_add_f32_e32 v125, v125, v40
	s_waitcnt vmcnt(4)
	v_mfma_f32_32x32x16_bf16 v[4:19], v[84:87], v[36:39], v[4:19]
	s_branch .LBB0_1082
